# attention: K-fragment LDS reads issued at the very top of the tile, ahead of the mask preparation and the next-tile request
# baseline (speedup 1.0000x reference)
; DEVI void attn_item(const P& p, int item, char* smem) {
;     ...
;             bf16x8 Kf[4][2];
; #pragma unroll
;             for (int n = 0; n < 4; ++n)
; #pragma unroll
;                 for (int kk = 0; kk < 2; ++kk) Kf[n][kk] = *(const bf16x8*)(sK + (16 * n + fr) * 128 + (((kk * 4 + fq) ^ (fr & 7)) << 4));
;             bf16x8 Pf[2][2];
; #pragma unroll
;             for (int m = 0; m < 2; ++m) {
;                 f32x4 s[4];
; #pragma unroll
;                 for (int n = 0; n < 4; ++n) {
;                     s[n] = (f32x4){0.f, 0.f, 0.f, 0.f};
; #pragma unroll
;                     for (int kk = 0; kk < 2; ++kk) s[n] = __builtin_amdgcn_mfma_f32_16x16x32_bf16(Kf[n][kk], Qf[m][kk], s[n], 0, 0, 0);
;                 }
;                 if (lat && (ti == 0 || ti == 4)) {
;                     const int qpos = q0 + mo + 16 * m + fr, kb = tok0 - CTX;
; #pragma unroll
;                     for (int n = 0; n < 4; ++n)
; #pragma unroll
;                         for (int j = 0; j < 4; ++j) {
;                             const int dd = qpos - (kb + 16 * n + 4 * fq + j);
;                             if (dd > 128 || dd < -128) s[n][j] = -1e30f;
;                         }
.Lat_inlds:
	ds_read_b128 v[70:73], v130
	ds_read_b128 v[62:65], v130 offset:2048
	ds_read_b128 v[54:57], v130 offset:4096
	ds_read_b128 v[82:85], v130 offset:6144
	ds_read_b128 v[94:97], v131
	ds_read_b128 v[90:93], v131 offset:2048
	ds_read_b128 v[86:89], v131 offset:4096
	ds_read_b128 v[66:69], v131 offset:6144
	s_and_b32 s4, s28, 11
	s_cmp_eq_u32 s4, 0
	s_cselect_b64 s[18:19], -1, 0
	s_and_b64 s[18:19], s[2:3], s[18:19]
	s_andn2_b64 vcc, exec, s[18:19]
	s_andn2_b64 s[2:3], exec, s[18:19]
	s_cbranch_vccnz .Lat_noprep
	v_sub_u32_e32 v0, s30, v140
	v_subrev_u32_e32 v171, s30, v142
	v_subrev_u32_e32 v170, s30, v143
	v_subrev_u32_e32 v168, s30, v144
	v_subrev_u32_e32 v169, s30, v145
	v_subrev_u32_e32 v165, s30, v146
	v_subrev_u32_e32 v162, s30, v147
	v_subrev_u32_e32 v166, s30, v148
	v_subrev_u32_e32 v163, s30, v149
	v_subrev_u32_e32 v167, s30, v150
	v_subrev_u32_e32 v164, s30, v151
	v_subrev_u32_e32 v161, s30, v140
	v_cmp_gt_u32_e64 s[4:5], s38, v0
	v_cmp_lt_u32_e64 s[6:7], s39, v171
	v_cmp_lt_u32_e64 s[8:9], s39, v170
	v_cmp_lt_u32_e64 s[10:11], s39, v168
	v_cmp_lt_u32_e64 s[12:13], s39, v169
	v_cmp_lt_u32_e64 s[14:15], s39, v165
	v_cmp_lt_u32_e64 s[16:17], s39, v162
	v_cmp_lt_u32_e64 s[20:21], s39, v163
	v_cmp_lt_u32_e64 s[22:23], s39, v167
	v_cmp_lt_u32_e64 s[24:25], s39, v164
	v_cmp_lt_u32_e64 s[56:57], s39, v166

; DEVI void attn_item(const P& p, int item, char* smem) {
;     ...
;             __syncthreads();
; #pragma unroll
;             for (int i = 0; i < 2; ++i) {
;                 const int row = (tid >> 3) + 32 * i, ch = tid & 7;
;                 const uint4 kv = *(const uint4*)(KB + ((size_t)(b * TPB + tok0 + row)) * 256 + kvh * 64 + ch * 8);
;                 *(uint4*)(sK + row * 128 + ((ch ^ (row & 7)) << 4)) = kv;
;                 const uint4 vv = *(const uint4*)(VT + ((size_t)(b * 256 + kvh * 64 + row)) * TPB + tok0 + ch * 8);
;                 *(uint4*)(sV + row * 128 + ((ch ^ ((row >> 1) & 7)) << 4)) = vv;
;             }
;             __syncthreads();
;             bf16x8 Kf[4][2];
; #pragma unroll
;             for (int n = 0; n < 4; ++n)
; #pragma unroll
;                 for (int kk = 0; kk < 2; ++kk) Kf[n][kk] = *(const bf16x8*)(sK + (16 * n + fr) * 128 + (((kk * 4 + fq) ^ (fr & 7)) << 4));
;             bf16x8 Pf[2][2];
; #pragma unroll
;             for (int m = 0; m < 2; ++m) {
;                 f32x4 s[4];
; #pragma unroll
;                 for (int n = 0; n < 4; ++n) {
;                     s[n] = (f32x4){0.f, 0.f, 0.f, 0.f};
; #pragma unroll
;                     for (int kk = 0; kk < 2; ++kk) s[n] = __builtin_amdgcn_mfma_f32_16x16x32_bf16(Kf[n][kk], Qf[m][kk], s[n], 0, 0, 0);
;                 }
;                 if (lat && (ti == 0 || ti == 4)) {
;                     const int qpos = q0 + mo + 16 * m + fr, kb = tok0 - CTX;
; #pragma unroll
;                     for (int n = 0; n < 4; ++n)
; #pragma unroll
;                         for (int j = 0; j < 4; ++j) {
;                             const int dd = qpos - (kb + 16 * n + 4 * fq + j);
;                             if (dd > 128 || dd < -128) s[n][j] = -1e30f;
;                         }
;                 }
.Lat_issue:
	s_mov_b32 s101, 0
	v_lshl_add_u64 v[252:253], s[100:101], 1, v[100:101]
	v_lshl_add_u64 v[254:255], v[252:253], 0, v[114:115]
	v_lshl_add_u64 v[250:251], v[252:253], 0, v[116:117]
	s_add_i32 s100, s100, s46
	s_lshl_b32 s100, s100, 9
	v_lshl_add_u64 v[248:249], v[226:227], 0, s[100:101]
	s_add_i32 s100, s100, 0x4000
	v_lshl_add_u64 v[252:253], v[226:227], 0, s[100:101]
	global_load_dwordx4 v[190:193], v[248:249], off
	global_load_dwordx4 v[194:197], v[254:255], off
	global_load_dwordx4 v[198:201], v[252:253], off
	global_load_dwordx4 v[202:205], v[250:251], off
	s_mov_b32 s99, 1
.Lat_nopf:
	s_waitcnt lgkmcnt(7)
	v_mfma_f32_16x16x32_bf16 v[50:53], v[70:73], v[22:25], 0
	s_waitcnt lgkmcnt(6)
	v_mfma_f32_16x16x32_bf16 v[58:61], v[62:65], v[22:25], 0
	s_waitcnt lgkmcnt(5)
	v_mfma_f32_16x16x32_bf16 v[182:185], v[54:57], v[22:25], 0
	s_waitcnt lgkmcnt(4)
	v_mfma_f32_16x16x32_bf16 v[186:189], v[82:85], v[22:25], 0
	s_waitcnt lgkmcnt(3)
	v_mfma_f32_16x16x32_bf16 v[78:81], v[94:97], v[26:29], v[50:53]
	s_waitcnt lgkmcnt(2)
	v_mfma_f32_16x16x32_bf16 v[74:77], v[90:93], v[26:29], v[58:61]
	s_waitcnt lgkmcnt(1)
	v_mfma_f32_16x16x32_bf16 v[58:61], v[86:89], v[26:29], v[182:185]
	s_waitcnt lgkmcnt(0)
	v_mfma_f32_16x16x32_bf16 v[50:53], v[66:69], v[26:29], v[186:189]
	s_cbranch_vccnz .LBB0_1442
	v_cmp_gt_u32_e32 vcc, s37, v161
	v_subrev_u32_e32 v173, s30, v152
	v_cndmask_b32_e64 v79, v136, v79, s[4:5]
	v_cndmask_b32_e32 v78, v78, v136, vcc
	v_cmp_lt_u32_e32 vcc, s39, v173
	v_subrev_u32_e32 v173, s30, v153
	v_cndmask_b32_e64 v80, v136, v80, s[6:7]
	v_cndmask_b32_e32 v50, v136, v50, vcc
	v_cmp_lt_u32_e32 vcc, s39, v173
	v_subrev_u32_e32 v173, s30, v154
	v_cndmask_b32_e64 v81, v136, v81, s[8:9]
	v_cndmask_b32_e32 v51, v136, v51, vcc
	v_cmp_lt_u32_e32 vcc, s39, v173
	v_subrev_u32_e32 v173, s30, v155
	v_cndmask_b32_e64 v74, v136, v74, s[10:11]
	v_cndmask_b32_e32 v52, v136, v52, vcc
	v_cmp_lt_u32_e32 vcc, s39, v173
	v_cndmask_b32_e64 v75, v136, v75, s[12:13]
	v_cndmask_b32_e64 v76, v136, v76, s[14:15]
	v_cndmask_b32_e64 v77, v136, v77, s[16:17]
	v_cndmask_b32_e64 v58, v136, v58, s[56:57]
	v_cndmask_b32_e64 v59, v136, v59, s[20:21]
	v_cndmask_b32_e64 v60, v136, v60, s[22:23]
	v_cndmask_b32_e64 v61, v136, v61, s[24:25]
	v_cndmask_b32_e32 v53, v136, v53, vcc
